# FFN-out sample panel: split-K partials stored as plain f32 slabs in workspace (no float atomics); final pass sums the 11 slabs + residual per row (one row per wave) and normalises
# speedup vs baseline: 1.0326x; 1.0326x over previous
.LBB0_736:
	s_add_i32 s36, s64, -1
	s_mul_i32 s36, s36, s82
	s_add_i32 s36, s36, s2
	s_addk_i32 s36, 0xfc00
	s_lshr_b32 s36, s36, 2
	s_lshl_b32 s36, s36, 20
	s_add_u32 s36, s36, 0x14d48800
	s_add_u32 s36, s80, s36
	s_addc_u32 s37, s81, 0
	v_ashrrev_i32_e32 v181, 31, v180
	v_ashrrev_i32_e32 v183, 31, v182
	v_lshlrev_b64 v[130:131], 12, v[180:181]
	v_lshl_add_u64 v[130:131], s[36:37], 0, v[130:131]
	v_lshlrev_b64 v[132:133], 2, v[182:183]
	v_lshl_add_u64 v[130:131], v[130:131], 0, v[132:133]
	global_store_dwordx4 v[130:131], v[126:129], off
	global_store_dwordx4 v[130:131], v[122:125], off offset:16
	global_store_dwordx4 v[130:131], v[110:113], off offset:512
	global_store_dwordx4 v[130:131], v[106:109], off offset:528
	s_nop 1
	v_or_b32_e32 v106, 16, v180
	v_ashrrev_i32_e32 v107, 31, v106
	v_lshlrev_b64 v[106:107], 12, v[106:107]
	v_lshl_add_u64 v[106:107], s[36:37], 0, v[106:107]
	v_lshl_add_u64 v[106:107], v[106:107], 0, v[132:133]
	global_store_dwordx4 v[106:107], v[118:121], off
	global_store_dwordx4 v[106:107], v[114:117], off offset:16
	global_store_dwordx4 v[106:107], v[94:97], off offset:512
	global_store_dwordx4 v[106:107], v[90:93], off offset:528
	s_nop 1
	v_or_b32_e32 v90, 32, v180
	v_ashrrev_i32_e32 v91, 31, v90
	v_lshlrev_b64 v[90:91], 12, v[90:91]
	v_lshl_add_u64 v[90:91], s[36:37], 0, v[90:91]
	v_lshl_add_u64 v[90:91], v[90:91], 0, v[132:133]
	global_store_dwordx4 v[90:91], v[102:105], off
	global_store_dwordx4 v[90:91], v[98:101], off offset:16
	global_store_dwordx4 v[90:91], v[78:81], off offset:512
	global_store_dwordx4 v[90:91], v[74:77], off offset:528
	s_nop 1
	v_or_b32_e32 v74, 48, v180
	v_ashrrev_i32_e32 v75, 31, v74
	v_lshlrev_b64 v[74:75], 12, v[74:75]
	v_lshl_add_u64 v[74:75], s[36:37], 0, v[74:75]
	v_lshl_add_u64 v[74:75], v[74:75], 0, v[132:133]
	global_store_dwordx4 v[74:75], v[86:89], off
	global_store_dwordx4 v[74:75], v[82:85], off offset:16
	global_store_dwordx4 v[74:75], v[70:73], off offset:512
	global_store_dwordx4 v[74:75], v[66:69], off offset:528
	s_nop 1
	v_add_co_u32_e32 v68, vcc, s70, v130
	v_lshl_add_u64 v[66:67], v[130:131], 0, s[26:27]
	s_nop 0
	v_addc_co_u32_e32 v69, vcc, 0, v131, vcc
	global_store_dwordx4 v[66:67], v[62:65], off
	global_store_dwordx4 v[66:67], v[58:61], off offset:16
	global_store_dwordx4 v[66:67], v[46:49], off offset:512
	global_store_dwordx4 v[66:67], v[42:45], off offset:528
	s_nop 1
	v_add_co_u32_e32 v44, vcc, s71, v130
	v_lshl_add_u64 v[42:43], v[130:131], 0, s[28:29]
	s_nop 0
	v_addc_co_u32_e32 v45, vcc, 0, v131, vcc
	global_store_dwordx4 v[42:43], v[54:57], off
	global_store_dwordx4 v[42:43], v[50:53], off offset:16
	global_store_dwordx4 v[42:43], v[30:33], off offset:512
	global_store_dwordx4 v[42:43], v[26:29], off offset:528
	s_nop 1
	v_add_co_u32_e32 v28, vcc, s72, v130
	v_lshl_add_u64 v[26:27], v[130:131], 0, s[30:31]
	s_nop 0
	v_addc_co_u32_e32 v29, vcc, 0, v131, vcc
	global_store_dwordx4 v[26:27], v[38:41], off
	global_store_dwordx4 v[26:27], v[34:37], off offset:16
	global_store_dwordx4 v[26:27], v[14:17], off offset:512
	global_store_dwordx4 v[26:27], v[10:13], off offset:528
	s_nop 1
	v_add_co_u32_e32 v12, vcc, s73, v130
	v_lshl_add_u64 v[10:11], v[130:131], 0, s[0:1]
	s_nop 0
	v_addc_co_u32_e32 v13, vcc, 0, v131, vcc
	global_store_dwordx4 v[10:11], v[22:25], off
	global_store_dwordx4 v[10:11], v[18:21], off offset:16
	global_store_dwordx4 v[10:11], v[6:9], off offset:512
	global_store_dwordx4 v[10:11], v[2:5], off offset:528
	s_nop 1
	s_and_b64 vcc, exec, s[6:7]
	s_mov_b64 s[6:7], -1
	s_cbranch_vccnz .LBB0_681
	s_branch .LBB0_742

.LBB0_797:
	s_or_b64 exec, exec, s[0:1]
	s_waitcnt lgkmcnt(0)
	s_barrier
	v_readlane_b32 s0, v252, 0
	v_ashrrev_i32_e32 v44, 6, v0
	v_and_b32_e32 v45, 63, v0
	v_add_u32_e32 v54, s0, v44
	s_nop 0
	v_readfirstlane_b32 s4, v54
	s_nop 3
	s_cmp_gt_u32 s4, 0xff
	s_cbranch_scc1 .Lsn_done
	s_lshl_b32 s5, s4, 12
	s_add_u32 s6, s78, s5
	s_addc_u32 s7, s79, 0
	s_add_u32 s6, s6, 0x10000000
	s_addc_u32 s7, s7, 0
	s_add_u32 s8, s80, s5
	s_addc_u32 s9, s81, 0
	s_add_u32 s8, s8, 0x24d48800
	s_addc_u32 s9, s9, 0
	v_lshlrev_b32_e32 v16, 4, v45
	global_load_dwordx4 v[0:3], v16, s[6:7]
	global_load_dwordx4 v[4:7], v16, s[6:7] offset:1024
	global_load_dwordx4 v[8:11], v16, s[6:7] offset:2048
	global_load_dwordx4 v[12:15], v16, s[6:7] offset:3072
	global_load_dwordx4 v[20:23], v16, s[76:77]
	global_load_dwordx4 v[24:27], v16, s[76:77] offset:1024
	global_load_dwordx4 v[28:31], v16, s[76:77] offset:2048
	global_load_dwordx4 v[32:35], v16, s[76:77] offset:3072
	global_load_dwordx4 v[56:59], v16, s[8:9]
	global_load_dwordx4 v[60:63], v16, s[8:9] offset:1024
	global_load_dwordx4 v[64:67], v16, s[8:9] offset:2048
	global_load_dwordx4 v[68:71], v16, s[8:9] offset:3072
	s_add_u32 s8, s8, 0x100000
	s_addc_u32 s9, s9, 0
	global_load_dwordx4 v[72:75], v16, s[8:9]
	global_load_dwordx4 v[76:79], v16, s[8:9] offset:1024
	global_load_dwordx4 v[80:83], v16, s[8:9] offset:2048
	global_load_dwordx4 v[84:87], v16, s[8:9] offset:3072
	s_add_u32 s8, s8, 0x100000
	s_addc_u32 s9, s9, 0
	global_load_dwordx4 v[88:91], v16, s[8:9]
	global_load_dwordx4 v[92:95], v16, s[8:9] offset:1024
	global_load_dwordx4 v[96:99], v16, s[8:9] offset:2048
	global_load_dwordx4 v[100:103], v16, s[8:9] offset:3072
	s_add_u32 s8, s8, 0x100000
	s_addc_u32 s9, s9, 0
	global_load_dwordx4 v[104:107], v16, s[8:9]
	global_load_dwordx4 v[108:111], v16, s[8:9] offset:1024
	global_load_dwordx4 v[112:115], v16, s[8:9] offset:2048
	global_load_dwordx4 v[116:119], v16, s[8:9] offset:3072
	s_add_u32 s8, s8, 0x100000
	s_addc_u32 s9, s9, 0
	global_load_dwordx4 v[120:123], v16, s[8:9]
	global_load_dwordx4 v[124:127], v16, s[8:9] offset:1024
	global_load_dwordx4 v[128:131], v16, s[8:9] offset:2048
	global_load_dwordx4 v[132:135], v16, s[8:9] offset:3072
	s_add_u32 s8, s8, 0x100000
	s_addc_u32 s9, s9, 0
	global_load_dwordx4 v[136:139], v16, s[8:9]
	global_load_dwordx4 v[140:143], v16, s[8:9] offset:1024
	global_load_dwordx4 v[144:147], v16, s[8:9] offset:2048
	global_load_dwordx4 v[148:151], v16, s[8:9] offset:3072
	s_add_u32 s8, s8, 0x100000
	s_addc_u32 s9, s9, 0
	global_load_dwordx4 v[152:155], v16, s[8:9]
	global_load_dwordx4 v[156:159], v16, s[8:9] offset:1024
	global_load_dwordx4 v[160:163], v16, s[8:9] offset:2048
	global_load_dwordx4 v[164:167], v16, s[8:9] offset:3072
	s_add_u32 s8, s8, 0x100000
	s_addc_u32 s9, s9, 0
	global_load_dwordx4 v[168:171], v16, s[8:9]
	global_load_dwordx4 v[172:175], v16, s[8:9] offset:1024
	global_load_dwordx4 v[176:179], v16, s[8:9] offset:2048
	global_load_dwordx4 v[180:183], v16, s[8:9] offset:3072
	s_add_u32 s8, s8, 0x100000
	s_addc_u32 s9, s9, 0
	global_load_dwordx4 v[184:187], v16, s[8:9]
	global_load_dwordx4 v[188:191], v16, s[8:9] offset:1024
	global_load_dwordx4 v[192:195], v16, s[8:9] offset:2048
	global_load_dwordx4 v[196:199], v16, s[8:9] offset:3072
	s_add_u32 s8, s8, 0x100000
	s_addc_u32 s9, s9, 0
	global_load_dwordx4 v[200:203], v16, s[8:9]
	global_load_dwordx4 v[204:207], v16, s[8:9] offset:1024
	global_load_dwordx4 v[212:215], v16, s[8:9] offset:2048
	global_load_dwordx4 v[216:219], v16, s[8:9] offset:3072
	s_add_u32 s8, s8, 0x100000
	s_addc_u32 s9, s9, 0
	global_load_dwordx4 v[220:223], v16, s[8:9]
	global_load_dwordx4 v[224:227], v16, s[8:9] offset:1024
	global_load_dwordx4 v[228:231], v16, s[8:9] offset:2048
	global_load_dwordx4 v[232:235], v16, s[8:9] offset:3072
	v_xor_b32_e32 v40, 1, v45
	v_xor_b32_e32 v41, 2, v45
	v_xor_b32_e32 v42, 4, v45
	v_xor_b32_e32 v43, 8, v45
	v_xor_b32_e32 v46, 16, v45
	v_xor_b32_e32 v47, 32, v45
	v_lshlrev_b32_e32 v40, 2, v40
	v_lshlrev_b32_e32 v41, 2, v41
	v_lshlrev_b32_e32 v42, 2, v42
	v_lshlrev_b32_e32 v43, 2, v43
	v_lshlrev_b32_e32 v46, 2, v46
	v_lshlrev_b32_e32 v47, 2, v47
	s_waitcnt vmcnt(0)
	v_pk_add_f32 v[0:1], v[0:1], v[56:57]
	v_pk_add_f32 v[2:3], v[2:3], v[58:59]
	v_pk_add_f32 v[4:5], v[4:5], v[60:61]
	v_pk_add_f32 v[6:7], v[6:7], v[62:63]
	v_pk_add_f32 v[8:9], v[8:9], v[64:65]
	v_pk_add_f32 v[10:11], v[10:11], v[66:67]
	v_pk_add_f32 v[12:13], v[12:13], v[68:69]
	v_pk_add_f32 v[14:15], v[14:15], v[70:71]
	v_pk_add_f32 v[0:1], v[0:1], v[72:73]
	v_pk_add_f32 v[2:3], v[2:3], v[74:75]
	v_pk_add_f32 v[4:5], v[4:5], v[76:77]
	v_pk_add_f32 v[6:7], v[6:7], v[78:79]
	v_pk_add_f32 v[8:9], v[8:9], v[80:81]
	v_pk_add_f32 v[10:11], v[10:11], v[82:83]
	v_pk_add_f32 v[12:13], v[12:13], v[84:85]
	v_pk_add_f32 v[14:15], v[14:15], v[86:87]
	v_pk_add_f32 v[0:1], v[0:1], v[88:89]
	v_pk_add_f32 v[2:3], v[2:3], v[90:91]
	v_pk_add_f32 v[4:5], v[4:5], v[92:93]
	v_pk_add_f32 v[6:7], v[6:7], v[94:95]
	v_pk_add_f32 v[8:9], v[8:9], v[96:97]
	v_pk_add_f32 v[10:11], v[10:11], v[98:99]
	v_pk_add_f32 v[12:13], v[12:13], v[100:101]
	v_pk_add_f32 v[14:15], v[14:15], v[102:103]
	v_pk_add_f32 v[0:1], v[0:1], v[104:105]
	v_pk_add_f32 v[2:3], v[2:3], v[106:107]
	v_pk_add_f32 v[4:5], v[4:5], v[108:109]
	v_pk_add_f32 v[6:7], v[6:7], v[110:111]
	v_pk_add_f32 v[8:9], v[8:9], v[112:113]
	v_pk_add_f32 v[10:11], v[10:11], v[114:115]
	v_pk_add_f32 v[12:13], v[12:13], v[116:117]
	v_pk_add_f32 v[14:15], v[14:15], v[118:119]
	v_pk_add_f32 v[0:1], v[0:1], v[120:121]
	v_pk_add_f32 v[2:3], v[2:3], v[122:123]
	v_pk_add_f32 v[4:5], v[4:5], v[124:125]
	v_pk_add_f32 v[6:7], v[6:7], v[126:127]
	v_pk_add_f32 v[8:9], v[8:9], v[128:129]
	v_pk_add_f32 v[10:11], v[10:11], v[130:131]
	v_pk_add_f32 v[12:13], v[12:13], v[132:133]
	v_pk_add_f32 v[14:15], v[14:15], v[134:135]
	v_pk_add_f32 v[0:1], v[0:1], v[136:137]
	v_pk_add_f32 v[2:3], v[2:3], v[138:139]
	v_pk_add_f32 v[4:5], v[4:5], v[140:141]
	v_pk_add_f32 v[6:7], v[6:7], v[142:143]
	v_pk_add_f32 v[8:9], v[8:9], v[144:145]
	v_pk_add_f32 v[10:11], v[10:11], v[146:147]
	v_pk_add_f32 v[12:13], v[12:13], v[148:149]
	v_pk_add_f32 v[14:15], v[14:15], v[150:151]
	v_pk_add_f32 v[0:1], v[0:1], v[152:153]
	v_pk_add_f32 v[2:3], v[2:3], v[154:155]
	v_pk_add_f32 v[4:5], v[4:5], v[156:157]
	v_pk_add_f32 v[6:7], v[6:7], v[158:159]
	v_pk_add_f32 v[8:9], v[8:9], v[160:161]
	v_pk_add_f32 v[10:11], v[10:11], v[162:163]
	v_pk_add_f32 v[12:13], v[12:13], v[164:165]
	v_pk_add_f32 v[14:15], v[14:15], v[166:167]
	v_pk_add_f32 v[0:1], v[0:1], v[168:169]
	v_pk_add_f32 v[2:3], v[2:3], v[170:171]
	v_pk_add_f32 v[4:5], v[4:5], v[172:173]
	v_pk_add_f32 v[6:7], v[6:7], v[174:175]
	v_pk_add_f32 v[8:9], v[8:9], v[176:177]
	v_pk_add_f32 v[10:11], v[10:11], v[178:179]
	v_pk_add_f32 v[12:13], v[12:13], v[180:181]
	v_pk_add_f32 v[14:15], v[14:15], v[182:183]
	v_pk_add_f32 v[0:1], v[0:1], v[184:185]
	v_pk_add_f32 v[2:3], v[2:3], v[186:187]
	v_pk_add_f32 v[4:5], v[4:5], v[188:189]
	v_pk_add_f32 v[6:7], v[6:7], v[190:191]
	v_pk_add_f32 v[8:9], v[8:9], v[192:193]
	v_pk_add_f32 v[10:11], v[10:11], v[194:195]
	v_pk_add_f32 v[12:13], v[12:13], v[196:197]
	v_pk_add_f32 v[14:15], v[14:15], v[198:199]
	v_pk_add_f32 v[0:1], v[0:1], v[200:201]
	v_pk_add_f32 v[2:3], v[2:3], v[202:203]
	v_pk_add_f32 v[4:5], v[4:5], v[204:205]
	v_pk_add_f32 v[6:7], v[6:7], v[206:207]
	v_pk_add_f32 v[8:9], v[8:9], v[212:213]
	v_pk_add_f32 v[10:11], v[10:11], v[214:215]
	v_pk_add_f32 v[12:13], v[12:13], v[216:217]
	v_pk_add_f32 v[14:15], v[14:15], v[218:219]
	v_pk_add_f32 v[0:1], v[0:1], v[220:221]
	v_pk_add_f32 v[2:3], v[2:3], v[222:223]
	v_pk_add_f32 v[4:5], v[4:5], v[224:225]
	v_pk_add_f32 v[6:7], v[6:7], v[226:227]
	v_pk_add_f32 v[8:9], v[8:9], v[228:229]
	v_pk_add_f32 v[10:11], v[10:11], v[230:231]
	v_pk_add_f32 v[12:13], v[12:13], v[232:233]
	v_pk_add_f32 v[14:15], v[14:15], v[234:235]
	v_mul_f32_e32 v17, v0, v0
	v_fmac_f32_e32 v17, v1, v1
	v_fmac_f32_e32 v17, v2, v2
	v_fmac_f32_e32 v17, v3, v3
	v_fmac_f32_e32 v17, v4, v4
	v_fmac_f32_e32 v17, v5, v5
	v_fmac_f32_e32 v17, v6, v6
	v_fmac_f32_e32 v17, v7, v7
	v_fmac_f32_e32 v17, v8, v8
	v_fmac_f32_e32 v17, v9, v9
	v_fmac_f32_e32 v17, v10, v10
	v_fmac_f32_e32 v17, v11, v11
	v_fmac_f32_e32 v17, v12, v12
	v_fmac_f32_e32 v17, v13, v13
	v_fmac_f32_e32 v17, v14, v14
	v_fmac_f32_e32 v17, v15, v15
	ds_bpermute_b32 v18, v40, v17
	s_waitcnt lgkmcnt(0)
	v_add_f32_e32 v17, v17, v18
	ds_bpermute_b32 v18, v41, v17
	s_waitcnt lgkmcnt(0)
	v_add_f32_e32 v17, v17, v18
	ds_bpermute_b32 v18, v42, v17
	s_waitcnt lgkmcnt(0)
	v_add_f32_e32 v17, v17, v18
	ds_bpermute_b32 v18, v43, v17
	s_waitcnt lgkmcnt(0)
	v_add_f32_e32 v17, v17, v18
	ds_bpermute_b32 v18, v46, v17
	s_waitcnt lgkmcnt(0)
	v_add_f32_e32 v17, v17, v18
	ds_bpermute_b32 v18, v47, v17
	s_waitcnt lgkmcnt(0)
	v_add_f32_e32 v17, v17, v18
	v_mov_b32_e32 v18, 0x358637bd
	v_fmac_f32_e32 v18, 0x3a800000, v17
	v_rsq_f32_e32 v18, v18
	s_nop 0
	v_mul_f32_e32 v0, v0, v18
	v_mul_f32_e32 v1, v1, v18
	v_mul_f32_e32 v2, v2, v18
	v_mul_f32_e32 v3, v3, v18
	v_mul_f32_e32 v4, v4, v18
	v_mul_f32_e32 v5, v5, v18
	v_mul_f32_e32 v6, v6, v18
	v_mul_f32_e32 v7, v7, v18
	v_mul_f32_e32 v8, v8, v18
	v_mul_f32_e32 v9, v9, v18
	v_mul_f32_e32 v10, v10, v18
	v_mul_f32_e32 v11, v11, v18
	v_mul_f32_e32 v12, v12, v18
	v_mul_f32_e32 v13, v13, v18
	v_mul_f32_e32 v14, v14, v18
	v_mul_f32_e32 v15, v15, v18
	v_pk_mul_f32 v[0:1], v[0:1], v[20:21]
	v_pk_mul_f32 v[2:3], v[2:3], v[22:23]
	v_pk_mul_f32 v[4:5], v[4:5], v[24:25]
	v_pk_mul_f32 v[6:7], v[6:7], v[26:27]
	v_pk_mul_f32 v[8:9], v[8:9], v[28:29]
	v_pk_mul_f32 v[10:11], v[10:11], v[30:31]
	v_pk_mul_f32 v[12:13], v[12:13], v[32:33]
	v_pk_mul_f32 v[14:15], v[14:15], v[34:35]
	global_store_dwordx4 v16, v[0:3], s[6:7]
	global_store_dwordx4 v16, v[4:7], s[6:7] offset:1024
	global_store_dwordx4 v16, v[8:11], s[6:7] offset:2048
	global_store_dwordx4 v16, v[12:15], s[6:7] offset:3072
.Lsn_done:
.LBB0_800:
	s_andn2_b64 vcc, exec, s[12:13]
	s_cbranch_vccnz .LBB0_804
	s_movk_i32 s0, 0x4000
	v_cmp_gt_i32_e32 vcc, s0, v54
	s_and_saveexec_b64 s[0:1], vcc
	s_cbranch_execz .LBB0_804
	v_lshlrev_b32_e32 v16, 5, v45
	global_load_dwordx4 v[0:3], v16, s[76:77] offset:16
	global_load_dwordx4 v[4:7], v16, s[76:77]
	global_load_dwordx4 v[8:11], v16, s[76:77] offset:2064
	global_load_dwordx4 v[12:15], v16, s[76:77] offset:2048
	v_mov_b32_e32 v17, 0
	v_lshlrev_b32_e32 v18, 4, v45
	v_mov_b32_e32 v19, v17
	v_lshl_add_u64 v[24:25], s[40:41], 0, v[18:19]
	v_and_b32_e32 v18, 64, v211
	v_add_u32_e32 v18, 64, v18
	v_xor_b32_e32 v19, 1, v211
	v_cmp_lt_i32_e32 vcc, v19, v18
	v_lshl_add_u64 v[26:27], s[78:79], 0, v[16:17]
	v_lshlrev_b32_e32 v16, 2, v44
	v_cndmask_b32_e32 v19, v211, v19, vcc
	v_lshlrev_b32_e32 v55, 2, v19
	v_xor_b32_e32 v19, 2, v211
	v_cmp_lt_i32_e32 vcc, v19, v18
	s_mov_b32 s0, 0x358637bd
	v_lshl_add_u32 v28, s2, 5, v16
	v_cndmask_b32_e32 v19, v211, v19, vcc
	v_lshlrev_b32_e32 v56, 2, v19
	v_xor_b32_e32 v19, 4, v211
	v_cmp_lt_i32_e32 vcc, v19, v18
	s_lshl_b32 s5, s82, 5
	s_mov_b64 s[2:3], 0
	v_cndmask_b32_e32 v19, v211, v19, vcc
	v_lshlrev_b32_e32 v57, 2, v19
	v_xor_b32_e32 v19, 8, v211
	v_cmp_lt_i32_e32 vcc, v19, v18
	s_mov_b32 s4, 0x3a800000
	s_mov_b32 s6, 0x800000
	v_cndmask_b32_e32 v19, v211, v19, vcc
	v_lshlrev_b32_e32 v58, 2, v19
	v_xor_b32_e32 v19, 16, v211
	v_cmp_lt_i32_e32 vcc, v19, v18
	s_movk_i32 s7, 0x3fff
	v_mov_b64_e32 v[30:31], s[0:1]
	v_cndmask_b32_e32 v19, v211, v19, vcc
	v_lshlrev_b32_e32 v59, 2, v19
	v_xor_b32_e32 v19, 32, v211
	v_cmp_lt_i32_e32 vcc, v19, v18
	s_nop 1
	v_cndmask_b32_e32 v18, v211, v19, vcc
	v_lshlrev_b32_e32 v60, 2, v18
